# weight conversion of layer-0 w_out/w_gu/w_down and all of layer 1 moved from phase 0 / w_in tail into layer 0's mix phase (blocks 256..351, CU partners of the latent-scan blocks)
# speedup vs baseline: 1.0743x; 1.0129x over previous
.LBB0_149:
	v_readlane_b32 s100, v242, 0
	s_movk_i32 s67, 0x80
	s_movk_i32 s66, 0x280
	s_sub_u32 s100, s100, 0x180
	s_waitcnt vmcnt(0) lgkmcnt(0)
	s_barrier
	v_readlane_b32 s0, v242, 42
	v_readlane_b32 s1, v242, 43
	v_readlane_b32 s4, v242, 3
	v_readlane_b32 s5, v242, 4
	v_lshrrev_b32_e32 v209, 6, v137
	v_and_b32_e32 v210, 63, v137
	s_sub_u32 s0, s0, 0x118
	s_subb_u32 s1, s1, 0
	v_lshrrev_b32_e32 v211, 3, v137
	v_and_b32_e32 v212, 7, v137
	v_mul_u32_u24_e32 v202, 65, v209
	v_mul_u32_u24_e32 v203, 0x208, v212
	v_add_u32_e32 v202, v202, v210
	v_add_u32_e32 v203, v203, v211
	v_lshlrev_b32_e32 v202, 2, v202
	v_lshlrev_b32_e32 v203, 2, v203
	v_lshlrev_b32_e32 v210, 2, v210
	v_lshlrev_b32_e32 v212, 4, v212
	v_add_u32_e32 v204, 0x400, v203
	v_add_u32_e32 v205, 0x80, v203
	v_add_u32_e32 v206, 0x480, v203
	s_cmp_ge_u32 s100, s66
	s_cbranch_scc1 .Lwc0_done
	s_cmpk_ge_u32 s100, 0x900
	s_cbranch_scc1 .Lwc0_t3_1
	s_cmpk_ge_u32 s100, 0x380
	s_cbranch_scc1 .Lwc0_t2_1
	s_cmpk_ge_u32 s100, 0x280
	s_cbranch_scc1 .Lwc0_t1_1
	s_movk_i32 s41, 0x78
	s_sub_u32 s99, s100, 0
	s_mul_i32 s44, s99, 0x66667
	s_lshr_b32 s44, s44, 24
	s_mul_i32 s36, s44, 40
	s_sub_u32 s99, s99, s36
	s_mul_i32 s38, s44, 0xa0000
	s_lshl_b32 s36, s99, 8
	s_add_u32 s38, s38, s36
	s_add_u32 s38, s38, 0x0
	s_lshl_b32 s36, s99, 6
	s_mov_b32 s32, 0x10000
	s_mul_i32 s36, s36, 0x800
	s_lshl_b32 s44, s44, 7
	s_add_u32 s36, s36, s44
	s_add_u32 s36, s36, 0x0
	s_mov_b32 s37, 0xa000
	s_movk_i32 s44, 0x800
	s_mov_b32 s99, 0x2800
	s_branch .Lwc0_tj_1

.Lxbi3_skip:
	s_barrier
	v_readlane_b32 s99, v242, 0
	s_nop 0
	s_sub_u32 s99, s99, 0x100
	s_cmpk_lt_u32 s99, 96
	s_cbranch_scc0 .Lwcm_skip
	s_add_u32 s100, s99, 0x280
	s_movk_i32 s23, 96
	s_movk_i32 s22, 0xbc0
	s_waitcnt vmcnt(0) lgkmcnt(0)
	s_barrier
	v_readlane_b32 s0, v242, 42
	v_readlane_b32 s1, v242, 43
	v_readlane_b32 s12, v242, 3
	v_readlane_b32 s13, v242, 4
	v_lshrrev_b32_e32 v217, 6, v137
	v_and_b32_e32 v218, 63, v137
	s_sub_u32 s0, s0, 0x118
	s_subb_u32 s1, s1, 0
	v_lshrrev_b32_e32 v219, 3, v137
	v_and_b32_e32 v220, 7, v137
	v_mul_u32_u24_e32 v210, 65, v217
	v_mul_u32_u24_e32 v211, 0x208, v220
	v_add_u32_e32 v210, v210, v218
	v_add_u32_e32 v211, v211, v219
	v_lshlrev_b32_e32 v210, 2, v210
	v_lshlrev_b32_e32 v211, 2, v211
	v_lshlrev_b32_e32 v218, 2, v218
	v_lshlrev_b32_e32 v220, 4, v220
	v_add_u32_e32 v212, 0x400, v211
	v_add_u32_e32 v213, 0x80, v211
	v_add_u32_e32 v214, 0x480, v211
	s_cmp_ge_u32 s100, s22
	s_cbranch_scc1 .Lwcm0_done
	s_cmpk_ge_u32 s100, 0x900
	s_cbranch_scc1 .Lwcm0_t3_1
	s_cmpk_ge_u32 s100, 0x380
	s_cbranch_scc1 .Lwcm0_t2_1
	s_cmpk_ge_u32 s100, 0x280
	s_cbranch_scc1 .Lwcm0_t1_1
	s_movk_i32 s14, 0x78
	s_sub_u32 s99, s100, 0
	s_mul_i32 s44, s99, 0x66667
	s_lshr_b32 s44, s44, 24
	s_mul_i32 s36, s44, 40
	s_sub_u32 s99, s99, s36
	s_mul_i32 s38, s44, 0xa0000
	s_lshl_b32 s36, s99, 8
	s_add_u32 s38, s38, s36
	s_add_u32 s38, s38, 0x0
	s_lshl_b32 s36, s99, 6
	s_mov_b32 s32, 0x10000
	s_mul_i32 s36, s36, 0x800
	s_lshl_b32 s44, s44, 7
	s_add_u32 s36, s36, s44
	s_add_u32 s36, s36, 0x0
	s_mov_b32 s37, 0xa000
	s_movk_i32 s44, 0x800
	s_mov_b32 s99, 0x2800
	s_branch .Lwcm0_tj_1
.Lwcm0_t1_1:
	s_movk_i32 s14, 0x80
	s_sub_u32 s99, s100, 640
	s_mul_i32 s44, s99, 0x100000
	s_lshr_b32 s44, s44, 24
	s_mul_i32 s36, s44, 16
	s_sub_u32 s99, s99, s36
	s_mul_i32 s38, s44, 0x40000
	s_lshl_b32 s36, s99, 8
	s_add_u32 s38, s38, s36
	s_add_u32 s38, s38, 0x0
	s_lshl_b32 s36, s99, 6
	s_mov_b32 s32, 0x10000
	s_mul_i32 s36, s36, 0x800
	s_lshl_b32 s44, s44, 7
	s_add_u32 s36, s36, s44
	s_add_u32 s36, s36, 0xa00000
	s_mov_b32 s37, 0x4000
	s_movk_i32 s44, 0x800
	s_mov_b32 s99, 0x1000
	s_branch .Lwcm0_tj_1
.Lwcm0_t2_1:
	s_movk_i32 s14, 0xf0
	s_sub_u32 s99, s100, 896
	s_mul_i32 s44, s99, 0x2e8bb
	s_lshr_b32 s44, s44, 24
	s_mul_i32 s36, s44, 88
	s_sub_u32 s99, s99, s36
	s_mul_i32 s38, s44, 0x160000
	s_lshl_b32 s36, s99, 8
	s_add_u32 s38, s38, s36
	s_add_u32 s38, s38, 0x0
	s_cmpk_ge_u32 s99, 44
	s_cselect_b32 s36, 44, 0
	s_cselect_b32 s37, 32, 0
	s_sub_u32 s36, s99, s36
	s_lshl_b32 s36, s36, 7
	s_add_u32 s36, s36, s37
	s_mov_b32 s32, 0x20000
	s_mul_i32 s36, s36, 0x800
	s_lshl_b32 s44, s44, 7
	s_add_u32 s36, s36, s44
	s_add_u32 s36, s36, 0xe00000
	s_mov_b32 s37, 0x16000
	s_movk_i32 s44, 0x800
	s_mov_b32 s99, 0x5800
	s_branch .Lwcm0_tj_1
.Lwcm0_t3_1:
	s_movk_i32 s14, 0xf8
	s_sub_u32 s99, s100, 2304
	s_mul_i32 s44, s99, 0x100000
	s_lshr_b32 s44, s44, 24
	s_mul_i32 s36, s44, 16
	s_sub_u32 s99, s99, s36
	s_mul_i32 s38, s44, 0x40000
	s_lshl_b32 s36, s99, 8
	s_add_u32 s38, s38, s36
	s_add_u32 s38, s38, 0x0
	s_lshl_b32 s36, s99, 6
	s_mov_b32 s32, 0x2c000
	s_mul_i32 s36, s36, 0x1600
	s_lshl_b32 s44, s44, 7
	s_add_u32 s36, s36, s44
	s_add_u32 s36, s36, 0x2400000
	s_mov_b32 s37, 0x4000
	s_movk_i32 s44, 0x1600
	s_mov_b32 s99, 0x1000
.Lwcm0_tj_1:
	s_load_dwordx2 s[8:9], s[0:1], s14
	s_add_u32 s20, s12, s36
	s_addc_u32 s21, s13, 0
	v_mad_u32_u24 v215, v217, s99, v218
	v_writelane_b32 v221, s20, 8
	v_writelane_b32 v221, s21, 9
	v_writelane_b32 v221, s32, 10
	v_writelane_b32 v221, s44, 11
	s_add_u32 s100, s100, s23
	s_waitcnt lgkmcnt(0)
	s_add_u32 s38, s8, s38
	s_addc_u32 s39, s9, 0
	global_load_dword v146, v215, s[38:39]
	s_add_u32 s38, s38, s37
	s_addc_u32 s39, s39, 0
	global_load_dword v147, v215, s[38:39]
	s_add_u32 s38, s38, s37
	s_addc_u32 s39, s39, 0
	global_load_dword v148, v215, s[38:39]
	s_add_u32 s38, s38, s37
	s_addc_u32 s39, s39, 0
	global_load_dword v149, v215, s[38:39]
	s_add_u32 s38, s38, s37
	s_addc_u32 s39, s39, 0
	global_load_dword v150, v215, s[38:39]
	s_add_u32 s38, s38, s37
	s_addc_u32 s39, s39, 0
	global_load_dword v151, v215, s[38:39]
	s_add_u32 s38, s38, s37
	s_addc_u32 s39, s39, 0
	global_load_dword v152, v215, s[38:39]
	s_add_u32 s38, s38, s37
	s_addc_u32 s39, s39, 0
	global_load_dword v153, v215, s[38:39]
	s_add_u32 s38, s38, s37
	s_addc_u32 s39, s39, 0
	global_load_dword v154, v215, s[38:39]
	s_add_u32 s38, s38, s37
	s_addc_u32 s39, s39, 0
	global_load_dword v155, v215, s[38:39]
	s_add_u32 s38, s38, s37
	s_addc_u32 s39, s39, 0
	global_load_dword v156, v215, s[38:39]
	s_add_u32 s38, s38, s37
	s_addc_u32 s39, s39, 0
	global_load_dword v157, v215, s[38:39]
	s_add_u32 s38, s38, s37
	s_addc_u32 s39, s39, 0
	global_load_dword v158, v215, s[38:39]
	s_add_u32 s38, s38, s37
	s_addc_u32 s39, s39, 0
	global_load_dword v159, v215, s[38:39]
	s_add_u32 s38, s38, s37
	s_addc_u32 s39, s39, 0
	global_load_dword v160, v215, s[38:39]
	s_add_u32 s38, s38, s37
	s_addc_u32 s39, s39, 0
	global_load_dword v161, v215, s[38:39]
	s_cmp_ge_u32 s100, s22
	s_cbranch_scc1 .Lwcm0_p1
	s_cmpk_ge_u32 s100, 0x900
	s_cbranch_scc1 .Lwcm0_t3_2
	s_cmpk_ge_u32 s100, 0x380
	s_cbranch_scc1 .Lwcm0_t2_2
	s_cmpk_ge_u32 s100, 0x280
	s_cbranch_scc1 .Lwcm0_t1_2
	s_movk_i32 s14, 0x78
	s_sub_u32 s99, s100, 0
	s_mul_i32 s44, s99, 0x66667
	s_lshr_b32 s44, s44, 24
	s_mul_i32 s36, s44, 40
	s_sub_u32 s99, s99, s36
	s_mul_i32 s38, s44, 0xa0000
	s_lshl_b32 s36, s99, 8
	s_add_u32 s38, s38, s36
	s_add_u32 s38, s38, 0x0
	s_lshl_b32 s36, s99, 6
	s_mov_b32 s32, 0x10000
	s_mul_i32 s36, s36, 0x800
	s_lshl_b32 s44, s44, 7
	s_add_u32 s36, s36, s44
	s_add_u32 s36, s36, 0x0
	s_mov_b32 s37, 0xa000
	s_movk_i32 s44, 0x800
	s_mov_b32 s99, 0x2800
	s_branch .Lwcm0_tj_2

.Lwcm0_tj_2:
	s_load_dwordx2 s[8:9], s[0:1], s14
	s_add_u32 s20, s12, s36
	s_addc_u32 s21, s13, 0
	v_mad_u32_u24 v215, v217, s99, v218
	v_writelane_b32 v221, s20, 12
	v_writelane_b32 v221, s21, 13
	v_writelane_b32 v221, s32, 14
	v_writelane_b32 v221, s44, 15
	s_add_u32 s100, s100, s23
	s_waitcnt lgkmcnt(0)
	s_add_u32 s38, s8, s38
	s_addc_u32 s39, s9, 0
	global_load_dword v162, v215, s[38:39]
	s_add_u32 s38, s38, s37
	s_addc_u32 s39, s39, 0
	global_load_dword v163, v215, s[38:39]
	s_add_u32 s38, s38, s37
	s_addc_u32 s39, s39, 0
	global_load_dword v164, v215, s[38:39]
	s_add_u32 s38, s38, s37
	s_addc_u32 s39, s39, 0
	global_load_dword v165, v215, s[38:39]
	s_add_u32 s38, s38, s37
	s_addc_u32 s39, s39, 0
	global_load_dword v166, v215, s[38:39]
	s_add_u32 s38, s38, s37
	s_addc_u32 s39, s39, 0
	global_load_dword v167, v215, s[38:39]
	s_add_u32 s38, s38, s37
	s_addc_u32 s39, s39, 0
	global_load_dword v168, v215, s[38:39]
	s_add_u32 s38, s38, s37
	s_addc_u32 s39, s39, 0
	global_load_dword v169, v215, s[38:39]
	s_add_u32 s38, s38, s37
	s_addc_u32 s39, s39, 0
	global_load_dword v170, v215, s[38:39]
	s_add_u32 s38, s38, s37
	s_addc_u32 s39, s39, 0
	global_load_dword v171, v215, s[38:39]
	s_add_u32 s38, s38, s37
	s_addc_u32 s39, s39, 0
	global_load_dword v172, v215, s[38:39]
	s_add_u32 s38, s38, s37
	s_addc_u32 s39, s39, 0
	global_load_dword v173, v215, s[38:39]
	s_add_u32 s38, s38, s37
	s_addc_u32 s39, s39, 0
	global_load_dword v174, v215, s[38:39]
	s_add_u32 s38, s38, s37
	s_addc_u32 s39, s39, 0
	global_load_dword v175, v215, s[38:39]
	s_add_u32 s38, s38, s37
	s_addc_u32 s39, s39, 0
	global_load_dword v176, v215, s[38:39]
	s_add_u32 s38, s38, s37
	s_addc_u32 s39, s39, 0
	global_load_dword v177, v215, s[38:39]
	s_cmp_ge_u32 s100, s22
	s_cbranch_scc1 .Lwcm0_p2
	s_cmpk_ge_u32 s100, 0x900
	s_cbranch_scc1 .Lwcm0_t3_3
	s_cmpk_ge_u32 s100, 0x380
	s_cbranch_scc1 .Lwcm0_t2_3
	s_cmpk_ge_u32 s100, 0x280
	s_cbranch_scc1 .Lwcm0_t1_3
	s_movk_i32 s14, 0x78
	s_sub_u32 s99, s100, 0
	s_mul_i32 s44, s99, 0x66667
	s_lshr_b32 s44, s44, 24
	s_mul_i32 s36, s44, 40
	s_sub_u32 s99, s99, s36
	s_mul_i32 s38, s44, 0xa0000
	s_lshl_b32 s36, s99, 8
	s_add_u32 s38, s38, s36
	s_add_u32 s38, s38, 0x0
	s_lshl_b32 s36, s99, 6
	s_mov_b32 s32, 0x10000
	s_mul_i32 s36, s36, 0x800
	s_lshl_b32 s44, s44, 7
	s_add_u32 s36, s36, s44
	s_add_u32 s36, s36, 0x0
	s_mov_b32 s37, 0xa000
	s_movk_i32 s44, 0x800
	s_mov_b32 s99, 0x2800
	s_branch .Lwcm0_tj_3

.Lwcm0_tj_3:
	s_load_dwordx2 s[8:9], s[0:1], s14
	s_add_u32 s20, s12, s36
	s_addc_u32 s21, s13, 0
	v_mad_u32_u24 v215, v217, s99, v218
	v_writelane_b32 v221, s20, 16
	v_writelane_b32 v221, s21, 17
	v_writelane_b32 v221, s32, 18
	v_writelane_b32 v221, s44, 19
	s_add_u32 s100, s100, s23
	s_waitcnt lgkmcnt(0)
	s_add_u32 s38, s8, s38
	s_addc_u32 s39, s9, 0
	global_load_dword v178, v215, s[38:39]
	s_add_u32 s38, s38, s37
	s_addc_u32 s39, s39, 0
	global_load_dword v179, v215, s[38:39]
	s_add_u32 s38, s38, s37
	s_addc_u32 s39, s39, 0
	global_load_dword v180, v215, s[38:39]
	s_add_u32 s38, s38, s37
	s_addc_u32 s39, s39, 0
	global_load_dword v181, v215, s[38:39]
	s_add_u32 s38, s38, s37
	s_addc_u32 s39, s39, 0
	global_load_dword v182, v215, s[38:39]
	s_add_u32 s38, s38, s37
	s_addc_u32 s39, s39, 0
	global_load_dword v183, v215, s[38:39]
	s_add_u32 s38, s38, s37
	s_addc_u32 s39, s39, 0
	global_load_dword v184, v215, s[38:39]
	s_add_u32 s38, s38, s37
	s_addc_u32 s39, s39, 0
	global_load_dword v185, v215, s[38:39]
	s_add_u32 s38, s38, s37
	s_addc_u32 s39, s39, 0
	global_load_dword v186, v215, s[38:39]
	s_add_u32 s38, s38, s37
	s_addc_u32 s39, s39, 0
	global_load_dword v187, v215, s[38:39]
	s_add_u32 s38, s38, s37
	s_addc_u32 s39, s39, 0
	global_load_dword v188, v215, s[38:39]
	s_add_u32 s38, s38, s37
	s_addc_u32 s39, s39, 0
	global_load_dword v189, v215, s[38:39]
	s_add_u32 s38, s38, s37
	s_addc_u32 s39, s39, 0
	global_load_dword v190, v215, s[38:39]
	s_add_u32 s38, s38, s37
	s_addc_u32 s39, s39, 0
	global_load_dword v191, v215, s[38:39]
	s_add_u32 s38, s38, s37
	s_addc_u32 s39, s39, 0
	global_load_dword v192, v215, s[38:39]
	s_add_u32 s38, s38, s37
	s_addc_u32 s39, s39, 0
	global_load_dword v193, v215, s[38:39]
.Lwcm0_loop:
	s_waitcnt vmcnt(32)
	v_readlane_b32 s20, v221, 8
	v_readlane_b32 s21, v221, 9
	v_readlane_b32 s32, v221, 10
	v_readlane_b32 s35, v221, 11
	ds_write_b32 v210, v146 offset:0
	ds_write_b32 v210, v147 offset:1040
	ds_write_b32 v210, v148 offset:2080
	ds_write_b32 v210, v149 offset:3120
	ds_write_b32 v210, v150 offset:4160
	ds_write_b32 v210, v151 offset:5200
	ds_write_b32 v210, v152 offset:6240
	ds_write_b32 v210, v153 offset:7280
	ds_write_b32 v210, v154 offset:8320
	ds_write_b32 v210, v155 offset:9360
	ds_write_b32 v210, v156 offset:10400
	ds_write_b32 v210, v157 offset:11440
	ds_write_b32 v210, v158 offset:12480
	ds_write_b32 v210, v159 offset:13520
	ds_write_b32 v210, v160 offset:14560
	ds_write_b32 v210, v161 offset:15600
	v_mad_u32_u24 v216, v219, s35, v220
	s_waitcnt lgkmcnt(0)
	s_barrier
	ds_read2_b32 v[194:195], v211 offset1:65
	ds_read2_b32 v[196:197], v211 offset0:130 offset1:195
	ds_read2_b32 v[198:199], v212 offset0:4 offset1:69
	ds_read2_b32 v[200:201], v212 offset0:134 offset1:199
	ds_read2_b32 v[202:203], v213 offset1:65
	ds_read2_b32 v[204:205], v213 offset0:130 offset1:195
	ds_read2_b32 v[206:207], v214 offset0:4 offset1:69
	ds_read2_b32 v[208:209], v214 offset0:134 offset1:199
	s_add_u32 s26, s20, s32
	s_addc_u32 s27, s21, 0
	s_waitcnt lgkmcnt(0)
	s_barrier
	v_cvt_pk_bf16_f32 v194, v194, v195
	v_cvt_pk_bf16_f32 v195, v196, v197
	v_cvt_pk_bf16_f32 v196, v198, v199
	v_cvt_pk_bf16_f32 v197, v200, v201
	v_cvt_pk_bf16_f32 v202, v202, v203
	v_cvt_pk_bf16_f32 v203, v204, v205
	v_cvt_pk_bf16_f32 v204, v206, v207
	v_cvt_pk_bf16_f32 v205, v208, v209
	global_store_dwordx4 v216, v[194:197], s[20:21]
	global_store_dwordx4 v216, v[202:205], s[26:27]
	s_cmp_ge_u32 s100, s22
	s_cbranch_scc1 .Lwcm0_tail0
	s_cmpk_ge_u32 s100, 0x900
	s_cbranch_scc1 .Lwcm0_t3_4
	s_cmpk_ge_u32 s100, 0x380
	s_cbranch_scc1 .Lwcm0_t2_4
	s_cmpk_ge_u32 s100, 0x280
	s_cbranch_scc1 .Lwcm0_t1_4
	s_movk_i32 s14, 0x78
	s_sub_u32 s99, s100, 0
	s_mul_i32 s44, s99, 0x66667
	s_lshr_b32 s44, s44, 24
	s_mul_i32 s36, s44, 40
	s_sub_u32 s99, s99, s36
	s_mul_i32 s38, s44, 0xa0000
	s_lshl_b32 s36, s99, 8
	s_add_u32 s38, s38, s36
	s_add_u32 s38, s38, 0x0
	s_lshl_b32 s36, s99, 6
	s_mov_b32 s32, 0x10000
	s_mul_i32 s36, s36, 0x800
	s_lshl_b32 s44, s44, 7
	s_add_u32 s36, s36, s44
	s_add_u32 s36, s36, 0x0
	s_mov_b32 s37, 0xa000
	s_movk_i32 s44, 0x800
	s_mov_b32 s99, 0x2800
	s_branch .Lwcm0_tj_4

.Lwcm0_tj_4:
	s_load_dwordx2 s[8:9], s[0:1], s14
	s_add_u32 s20, s12, s36
	s_addc_u32 s21, s13, 0
	v_mad_u32_u24 v215, v217, s99, v218
	v_writelane_b32 v221, s20, 8
	v_writelane_b32 v221, s21, 9
	v_writelane_b32 v221, s32, 10
	v_writelane_b32 v221, s44, 11
	s_add_u32 s100, s100, s23
	s_waitcnt lgkmcnt(0)
	s_add_u32 s38, s8, s38
	s_addc_u32 s39, s9, 0
	global_load_dword v146, v215, s[38:39]
	s_add_u32 s38, s38, s37
	s_addc_u32 s39, s39, 0
	global_load_dword v147, v215, s[38:39]
	s_add_u32 s38, s38, s37
	s_addc_u32 s39, s39, 0
	global_load_dword v148, v215, s[38:39]
	s_add_u32 s38, s38, s37
	s_addc_u32 s39, s39, 0
	global_load_dword v149, v215, s[38:39]
	s_add_u32 s38, s38, s37
	s_addc_u32 s39, s39, 0
	global_load_dword v150, v215, s[38:39]
	s_add_u32 s38, s38, s37
	s_addc_u32 s39, s39, 0
	global_load_dword v151, v215, s[38:39]
	s_add_u32 s38, s38, s37
	s_addc_u32 s39, s39, 0
	global_load_dword v152, v215, s[38:39]
	s_add_u32 s38, s38, s37
	s_addc_u32 s39, s39, 0
	global_load_dword v153, v215, s[38:39]
	s_add_u32 s38, s38, s37
	s_addc_u32 s39, s39, 0
	global_load_dword v154, v215, s[38:39]
	s_add_u32 s38, s38, s37
	s_addc_u32 s39, s39, 0
	global_load_dword v155, v215, s[38:39]
	s_add_u32 s38, s38, s37
	s_addc_u32 s39, s39, 0
	global_load_dword v156, v215, s[38:39]
	s_add_u32 s38, s38, s37
	s_addc_u32 s39, s39, 0
	global_load_dword v157, v215, s[38:39]
	s_add_u32 s38, s38, s37
	s_addc_u32 s39, s39, 0
	global_load_dword v158, v215, s[38:39]
	s_add_u32 s38, s38, s37
	s_addc_u32 s39, s39, 0
	global_load_dword v159, v215, s[38:39]
	s_add_u32 s38, s38, s37
	s_addc_u32 s39, s39, 0
	global_load_dword v160, v215, s[38:39]
	s_add_u32 s38, s38, s37
	s_addc_u32 s39, s39, 0
	global_load_dword v161, v215, s[38:39]
	s_waitcnt vmcnt(32)
	v_readlane_b32 s20, v221, 12
	v_readlane_b32 s21, v221, 13
	v_readlane_b32 s32, v221, 14
	v_readlane_b32 s35, v221, 15
	ds_write_b32 v210, v162 offset:0
	ds_write_b32 v210, v163 offset:1040
	ds_write_b32 v210, v164 offset:2080
	ds_write_b32 v210, v165 offset:3120
	ds_write_b32 v210, v166 offset:4160
	ds_write_b32 v210, v167 offset:5200
	ds_write_b32 v210, v168 offset:6240
	ds_write_b32 v210, v169 offset:7280
	ds_write_b32 v210, v170 offset:8320
	ds_write_b32 v210, v171 offset:9360
	ds_write_b32 v210, v172 offset:10400
	ds_write_b32 v210, v173 offset:11440
	ds_write_b32 v210, v174 offset:12480
	ds_write_b32 v210, v175 offset:13520
	ds_write_b32 v210, v176 offset:14560
	ds_write_b32 v210, v177 offset:15600
	v_mad_u32_u24 v216, v219, s35, v220
	s_waitcnt lgkmcnt(0)
	s_barrier
	ds_read2_b32 v[194:195], v211 offset1:65
	ds_read2_b32 v[196:197], v211 offset0:130 offset1:195
	ds_read2_b32 v[198:199], v212 offset0:4 offset1:69
	ds_read2_b32 v[200:201], v212 offset0:134 offset1:199
	ds_read2_b32 v[202:203], v213 offset1:65
	ds_read2_b32 v[204:205], v213 offset0:130 offset1:195
	ds_read2_b32 v[206:207], v214 offset0:4 offset1:69
	ds_read2_b32 v[208:209], v214 offset0:134 offset1:199
	s_add_u32 s26, s20, s32
	s_addc_u32 s27, s21, 0
	s_waitcnt lgkmcnt(0)
	s_barrier
	v_cvt_pk_bf16_f32 v194, v194, v195
	v_cvt_pk_bf16_f32 v195, v196, v197
	v_cvt_pk_bf16_f32 v196, v198, v199
	v_cvt_pk_bf16_f32 v197, v200, v201
	v_cvt_pk_bf16_f32 v202, v202, v203
	v_cvt_pk_bf16_f32 v203, v204, v205
	v_cvt_pk_bf16_f32 v204, v206, v207
	v_cvt_pk_bf16_f32 v205, v208, v209
	global_store_dwordx4 v216, v[194:197], s[20:21]
	global_store_dwordx4 v216, v[202:205], s[26:27]
	s_cmp_ge_u32 s100, s22
	s_cbranch_scc1 .Lwcm0_tail1
	s_cmpk_ge_u32 s100, 0x900
	s_cbranch_scc1 .Lwcm0_t3_5
	s_cmpk_ge_u32 s100, 0x380
	s_cbranch_scc1 .Lwcm0_t2_5
	s_cmpk_ge_u32 s100, 0x280
	s_cbranch_scc1 .Lwcm0_t1_5
	s_movk_i32 s14, 0x78
	s_sub_u32 s99, s100, 0
	s_mul_i32 s44, s99, 0x66667
	s_lshr_b32 s44, s44, 24
	s_mul_i32 s36, s44, 40
	s_sub_u32 s99, s99, s36
	s_mul_i32 s38, s44, 0xa0000
	s_lshl_b32 s36, s99, 8
	s_add_u32 s38, s38, s36
	s_add_u32 s38, s38, 0x0
	s_lshl_b32 s36, s99, 6
	s_mov_b32 s32, 0x10000
	s_mul_i32 s36, s36, 0x800
	s_lshl_b32 s44, s44, 7
	s_add_u32 s36, s36, s44
	s_add_u32 s36, s36, 0x0
	s_mov_b32 s37, 0xa000
	s_movk_i32 s44, 0x800
	s_mov_b32 s99, 0x2800
	s_branch .Lwcm0_tj_5

.Lwcm0_tj_5:
	s_load_dwordx2 s[8:9], s[0:1], s14
	s_add_u32 s20, s12, s36
	s_addc_u32 s21, s13, 0
	v_mad_u32_u24 v215, v217, s99, v218
	v_writelane_b32 v221, s20, 12
	v_writelane_b32 v221, s21, 13
	v_writelane_b32 v221, s32, 14
	v_writelane_b32 v221, s44, 15
	s_add_u32 s100, s100, s23
	s_waitcnt lgkmcnt(0)
	s_add_u32 s38, s8, s38
	s_addc_u32 s39, s9, 0
	global_load_dword v162, v215, s[38:39]
	s_add_u32 s38, s38, s37
	s_addc_u32 s39, s39, 0
	global_load_dword v163, v215, s[38:39]
	s_add_u32 s38, s38, s37
	s_addc_u32 s39, s39, 0
	global_load_dword v164, v215, s[38:39]
	s_add_u32 s38, s38, s37
	s_addc_u32 s39, s39, 0
	global_load_dword v165, v215, s[38:39]
	s_add_u32 s38, s38, s37
	s_addc_u32 s39, s39, 0
	global_load_dword v166, v215, s[38:39]
	s_add_u32 s38, s38, s37
	s_addc_u32 s39, s39, 0
	global_load_dword v167, v215, s[38:39]
	s_add_u32 s38, s38, s37
	s_addc_u32 s39, s39, 0
	global_load_dword v168, v215, s[38:39]
	s_add_u32 s38, s38, s37
	s_addc_u32 s39, s39, 0
	global_load_dword v169, v215, s[38:39]
	s_add_u32 s38, s38, s37
	s_addc_u32 s39, s39, 0
	global_load_dword v170, v215, s[38:39]
	s_add_u32 s38, s38, s37
	s_addc_u32 s39, s39, 0
	global_load_dword v171, v215, s[38:39]
	s_add_u32 s38, s38, s37
	s_addc_u32 s39, s39, 0
	global_load_dword v172, v215, s[38:39]
	s_add_u32 s38, s38, s37
	s_addc_u32 s39, s39, 0
	global_load_dword v173, v215, s[38:39]
	s_add_u32 s38, s38, s37
	s_addc_u32 s39, s39, 0
	global_load_dword v174, v215, s[38:39]
	s_add_u32 s38, s38, s37
	s_addc_u32 s39, s39, 0
	global_load_dword v175, v215, s[38:39]
	s_add_u32 s38, s38, s37
	s_addc_u32 s39, s39, 0
	global_load_dword v176, v215, s[38:39]
	s_add_u32 s38, s38, s37
	s_addc_u32 s39, s39, 0
	global_load_dword v177, v215, s[38:39]
	s_waitcnt vmcnt(32)
	v_readlane_b32 s20, v221, 16
	v_readlane_b32 s21, v221, 17
	v_readlane_b32 s32, v221, 18
	v_readlane_b32 s35, v221, 19
	ds_write_b32 v210, v178 offset:0
	ds_write_b32 v210, v179 offset:1040
	ds_write_b32 v210, v180 offset:2080
	ds_write_b32 v210, v181 offset:3120
	ds_write_b32 v210, v182 offset:4160
	ds_write_b32 v210, v183 offset:5200
	ds_write_b32 v210, v184 offset:6240
	ds_write_b32 v210, v185 offset:7280
	ds_write_b32 v210, v186 offset:8320
	ds_write_b32 v210, v187 offset:9360
	ds_write_b32 v210, v188 offset:10400
	ds_write_b32 v210, v189 offset:11440
	ds_write_b32 v210, v190 offset:12480
	ds_write_b32 v210, v191 offset:13520
	ds_write_b32 v210, v192 offset:14560
	ds_write_b32 v210, v193 offset:15600
	v_mad_u32_u24 v216, v219, s35, v220
	s_waitcnt lgkmcnt(0)
	s_barrier
	ds_read2_b32 v[194:195], v211 offset1:65
	ds_read2_b32 v[196:197], v211 offset0:130 offset1:195
	ds_read2_b32 v[198:199], v212 offset0:4 offset1:69
	ds_read2_b32 v[200:201], v212 offset0:134 offset1:199
	ds_read2_b32 v[202:203], v213 offset1:65
	ds_read2_b32 v[204:205], v213 offset0:130 offset1:195
	ds_read2_b32 v[206:207], v214 offset0:4 offset1:69
	ds_read2_b32 v[208:209], v214 offset0:134 offset1:199
	s_add_u32 s26, s20, s32
	s_addc_u32 s27, s21, 0
	s_waitcnt lgkmcnt(0)
	s_barrier
	v_cvt_pk_bf16_f32 v194, v194, v195
	v_cvt_pk_bf16_f32 v195, v196, v197
	v_cvt_pk_bf16_f32 v196, v198, v199
	v_cvt_pk_bf16_f32 v197, v200, v201
	v_cvt_pk_bf16_f32 v202, v202, v203
	v_cvt_pk_bf16_f32 v203, v204, v205
	v_cvt_pk_bf16_f32 v204, v206, v207
	v_cvt_pk_bf16_f32 v205, v208, v209
	global_store_dwordx4 v216, v[194:197], s[20:21]
	global_store_dwordx4 v216, v[202:205], s[26:27]
	s_cmp_ge_u32 s100, s22
	s_cbranch_scc1 .Lwcm0_tail2
	s_cmpk_ge_u32 s100, 0x900
	s_cbranch_scc1 .Lwcm0_t3_6
	s_cmpk_ge_u32 s100, 0x380
	s_cbranch_scc1 .Lwcm0_t2_6
	s_cmpk_ge_u32 s100, 0x280
	s_cbranch_scc1 .Lwcm0_t1_6
	s_movk_i32 s14, 0x78
	s_sub_u32 s99, s100, 0
	s_mul_i32 s44, s99, 0x66667
	s_lshr_b32 s44, s44, 24
	s_mul_i32 s36, s44, 40
	s_sub_u32 s99, s99, s36
	s_mul_i32 s38, s44, 0xa0000
	s_lshl_b32 s36, s99, 8
	s_add_u32 s38, s38, s36
	s_add_u32 s38, s38, 0x0
	s_lshl_b32 s36, s99, 6
	s_mov_b32 s32, 0x10000
	s_mul_i32 s36, s36, 0x800
	s_lshl_b32 s44, s44, 7
	s_add_u32 s36, s36, s44
	s_add_u32 s36, s36, 0x0
	s_mov_b32 s37, 0xa000
	s_movk_i32 s44, 0x800
	s_mov_b32 s99, 0x2800
	s_branch .Lwcm0_tj_6

.Lwcm0_tj_6:
	s_load_dwordx2 s[8:9], s[0:1], s14
	s_add_u32 s20, s12, s36
	s_addc_u32 s21, s13, 0
	v_mad_u32_u24 v215, v217, s99, v218
	v_writelane_b32 v221, s20, 16
	v_writelane_b32 v221, s21, 17
	v_writelane_b32 v221, s32, 18
	v_writelane_b32 v221, s44, 19
	s_add_u32 s100, s100, s23
	s_waitcnt lgkmcnt(0)
	s_add_u32 s38, s8, s38
	s_addc_u32 s39, s9, 0
	global_load_dword v178, v215, s[38:39]
	s_add_u32 s38, s38, s37
	s_addc_u32 s39, s39, 0
	global_load_dword v179, v215, s[38:39]
	s_add_u32 s38, s38, s37
	s_addc_u32 s39, s39, 0
	global_load_dword v180, v215, s[38:39]
	s_add_u32 s38, s38, s37
	s_addc_u32 s39, s39, 0
	global_load_dword v181, v215, s[38:39]
	s_add_u32 s38, s38, s37
	s_addc_u32 s39, s39, 0
	global_load_dword v182, v215, s[38:39]
	s_add_u32 s38, s38, s37
	s_addc_u32 s39, s39, 0
	global_load_dword v183, v215, s[38:39]
	s_add_u32 s38, s38, s37
	s_addc_u32 s39, s39, 0
	global_load_dword v184, v215, s[38:39]
	s_add_u32 s38, s38, s37
	s_addc_u32 s39, s39, 0
	global_load_dword v185, v215, s[38:39]
	s_add_u32 s38, s38, s37
	s_addc_u32 s39, s39, 0
	global_load_dword v186, v215, s[38:39]
	s_add_u32 s38, s38, s37
	s_addc_u32 s39, s39, 0
	global_load_dword v187, v215, s[38:39]
	s_add_u32 s38, s38, s37
	s_addc_u32 s39, s39, 0
	global_load_dword v188, v215, s[38:39]
	s_add_u32 s38, s38, s37
	s_addc_u32 s39, s39, 0
	global_load_dword v189, v215, s[38:39]
	s_add_u32 s38, s38, s37
	s_addc_u32 s39, s39, 0
	global_load_dword v190, v215, s[38:39]
	s_add_u32 s38, s38, s37
	s_addc_u32 s39, s39, 0
	global_load_dword v191, v215, s[38:39]
	s_add_u32 s38, s38, s37
	s_addc_u32 s39, s39, 0
	global_load_dword v192, v215, s[38:39]
	s_add_u32 s38, s38, s37
	s_addc_u32 s39, s39, 0
	global_load_dword v193, v215, s[38:39]
	s_branch .Lwcm0_loop
.Lwcm0_tail0:
	s_waitcnt vmcnt(0)
	v_readlane_b32 s20, v221, 12
	v_readlane_b32 s21, v221, 13
	v_readlane_b32 s32, v221, 14
	v_readlane_b32 s35, v221, 15
	ds_write_b32 v210, v162 offset:0
	ds_write_b32 v210, v163 offset:1040
	ds_write_b32 v210, v164 offset:2080
	ds_write_b32 v210, v165 offset:3120
	ds_write_b32 v210, v166 offset:4160
	ds_write_b32 v210, v167 offset:5200
	ds_write_b32 v210, v168 offset:6240
	ds_write_b32 v210, v169 offset:7280
	ds_write_b32 v210, v170 offset:8320
	ds_write_b32 v210, v171 offset:9360
	ds_write_b32 v210, v172 offset:10400
	ds_write_b32 v210, v173 offset:11440
	ds_write_b32 v210, v174 offset:12480
	ds_write_b32 v210, v175 offset:13520
	ds_write_b32 v210, v176 offset:14560
	ds_write_b32 v210, v177 offset:15600
	v_mad_u32_u24 v216, v219, s35, v220
	s_waitcnt lgkmcnt(0)
	s_barrier
	ds_read2_b32 v[194:195], v211 offset1:65
	ds_read2_b32 v[196:197], v211 offset0:130 offset1:195
	ds_read2_b32 v[198:199], v212 offset0:4 offset1:69
	ds_read2_b32 v[200:201], v212 offset0:134 offset1:199
	ds_read2_b32 v[202:203], v213 offset1:65
	ds_read2_b32 v[204:205], v213 offset0:130 offset1:195
	ds_read2_b32 v[206:207], v214 offset0:4 offset1:69
	ds_read2_b32 v[208:209], v214 offset0:134 offset1:199
	s_add_u32 s26, s20, s32
	s_addc_u32 s27, s21, 0
	s_waitcnt lgkmcnt(0)
	s_barrier
	v_cvt_pk_bf16_f32 v194, v194, v195
	v_cvt_pk_bf16_f32 v195, v196, v197
	v_cvt_pk_bf16_f32 v196, v198, v199
	v_cvt_pk_bf16_f32 v197, v200, v201
	v_cvt_pk_bf16_f32 v202, v202, v203
	v_cvt_pk_bf16_f32 v203, v204, v205
	v_cvt_pk_bf16_f32 v204, v206, v207
	v_cvt_pk_bf16_f32 v205, v208, v209
	global_store_dwordx4 v216, v[194:197], s[20:21]
	global_store_dwordx4 v216, v[202:205], s[26:27]
	v_readlane_b32 s20, v221, 16
	v_readlane_b32 s21, v221, 17
	v_readlane_b32 s32, v221, 18
	v_readlane_b32 s35, v221, 19
	ds_write_b32 v210, v178 offset:0
	ds_write_b32 v210, v179 offset:1040
	ds_write_b32 v210, v180 offset:2080
	ds_write_b32 v210, v181 offset:3120
	ds_write_b32 v210, v182 offset:4160
	ds_write_b32 v210, v183 offset:5200
	ds_write_b32 v210, v184 offset:6240
	ds_write_b32 v210, v185 offset:7280
	ds_write_b32 v210, v186 offset:8320
	ds_write_b32 v210, v187 offset:9360
	ds_write_b32 v210, v188 offset:10400
	ds_write_b32 v210, v189 offset:11440
	ds_write_b32 v210, v190 offset:12480
	ds_write_b32 v210, v191 offset:13520
	ds_write_b32 v210, v192 offset:14560
	ds_write_b32 v210, v193 offset:15600
	v_mad_u32_u24 v216, v219, s35, v220
	s_waitcnt lgkmcnt(0)
	s_barrier
	ds_read2_b32 v[194:195], v211 offset1:65
	ds_read2_b32 v[196:197], v211 offset0:130 offset1:195
	ds_read2_b32 v[198:199], v212 offset0:4 offset1:69
	ds_read2_b32 v[200:201], v212 offset0:134 offset1:199
	ds_read2_b32 v[202:203], v213 offset1:65
	ds_read2_b32 v[204:205], v213 offset0:130 offset1:195
	ds_read2_b32 v[206:207], v214 offset0:4 offset1:69
	ds_read2_b32 v[208:209], v214 offset0:134 offset1:199
	s_add_u32 s26, s20, s32
	s_addc_u32 s27, s21, 0
	s_waitcnt lgkmcnt(0)
	s_barrier
	v_cvt_pk_bf16_f32 v194, v194, v195
	v_cvt_pk_bf16_f32 v195, v196, v197
	v_cvt_pk_bf16_f32 v196, v198, v199
	v_cvt_pk_bf16_f32 v197, v200, v201
	v_cvt_pk_bf16_f32 v202, v202, v203
	v_cvt_pk_bf16_f32 v203, v204, v205
	v_cvt_pk_bf16_f32 v204, v206, v207
	v_cvt_pk_bf16_f32 v205, v208, v209
	global_store_dwordx4 v216, v[194:197], s[20:21]
	global_store_dwordx4 v216, v[202:205], s[26:27]
	s_branch .Lwcm0_done
.Lwcm0_tail1:
	s_waitcnt vmcnt(0)
	v_readlane_b32 s20, v221, 16
	v_readlane_b32 s21, v221, 17
	v_readlane_b32 s32, v221, 18
	v_readlane_b32 s35, v221, 19
	ds_write_b32 v210, v178 offset:0
	ds_write_b32 v210, v179 offset:1040
	ds_write_b32 v210, v180 offset:2080
	ds_write_b32 v210, v181 offset:3120
	ds_write_b32 v210, v182 offset:4160
	ds_write_b32 v210, v183 offset:5200
	ds_write_b32 v210, v184 offset:6240
	ds_write_b32 v210, v185 offset:7280
	ds_write_b32 v210, v186 offset:8320
	ds_write_b32 v210, v187 offset:9360
	ds_write_b32 v210, v188 offset:10400
	ds_write_b32 v210, v189 offset:11440
	ds_write_b32 v210, v190 offset:12480
	ds_write_b32 v210, v191 offset:13520
	ds_write_b32 v210, v192 offset:14560
	ds_write_b32 v210, v193 offset:15600
	v_mad_u32_u24 v216, v219, s35, v220
	s_waitcnt lgkmcnt(0)
	s_barrier
	ds_read2_b32 v[194:195], v211 offset1:65
	ds_read2_b32 v[196:197], v211 offset0:130 offset1:195
	ds_read2_b32 v[198:199], v212 offset0:4 offset1:69
	ds_read2_b32 v[200:201], v212 offset0:134 offset1:199
	ds_read2_b32 v[202:203], v213 offset1:65
	ds_read2_b32 v[204:205], v213 offset0:130 offset1:195
	ds_read2_b32 v[206:207], v214 offset0:4 offset1:69
	ds_read2_b32 v[208:209], v214 offset0:134 offset1:199
	s_add_u32 s26, s20, s32
	s_addc_u32 s27, s21, 0
	s_waitcnt lgkmcnt(0)
	s_barrier
	v_cvt_pk_bf16_f32 v194, v194, v195
	v_cvt_pk_bf16_f32 v195, v196, v197
	v_cvt_pk_bf16_f32 v196, v198, v199
	v_cvt_pk_bf16_f32 v197, v200, v201
	v_cvt_pk_bf16_f32 v202, v202, v203
	v_cvt_pk_bf16_f32 v203, v204, v205
	v_cvt_pk_bf16_f32 v204, v206, v207
	v_cvt_pk_bf16_f32 v205, v208, v209
	global_store_dwordx4 v216, v[194:197], s[20:21]
	global_store_dwordx4 v216, v[202:205], s[26:27]
	v_readlane_b32 s20, v221, 8
	v_readlane_b32 s21, v221, 9
	v_readlane_b32 s32, v221, 10
	v_readlane_b32 s35, v221, 11
	ds_write_b32 v210, v146 offset:0
	ds_write_b32 v210, v147 offset:1040
	ds_write_b32 v210, v148 offset:2080
	ds_write_b32 v210, v149 offset:3120
	ds_write_b32 v210, v150 offset:4160
	ds_write_b32 v210, v151 offset:5200
	ds_write_b32 v210, v152 offset:6240
	ds_write_b32 v210, v153 offset:7280
	ds_write_b32 v210, v154 offset:8320
	ds_write_b32 v210, v155 offset:9360
	ds_write_b32 v210, v156 offset:10400
	ds_write_b32 v210, v157 offset:11440
	ds_write_b32 v210, v158 offset:12480
	ds_write_b32 v210, v159 offset:13520
	ds_write_b32 v210, v160 offset:14560
	ds_write_b32 v210, v161 offset:15600
	v_mad_u32_u24 v216, v219, s35, v220
	s_waitcnt lgkmcnt(0)
	s_barrier
	ds_read2_b32 v[194:195], v211 offset1:65
	ds_read2_b32 v[196:197], v211 offset0:130 offset1:195
	ds_read2_b32 v[198:199], v212 offset0:4 offset1:69
	ds_read2_b32 v[200:201], v212 offset0:134 offset1:199
	ds_read2_b32 v[202:203], v213 offset1:65
	ds_read2_b32 v[204:205], v213 offset0:130 offset1:195
	ds_read2_b32 v[206:207], v214 offset0:4 offset1:69
	ds_read2_b32 v[208:209], v214 offset0:134 offset1:199
	s_add_u32 s26, s20, s32
	s_addc_u32 s27, s21, 0
	s_waitcnt lgkmcnt(0)
	s_barrier
	v_cvt_pk_bf16_f32 v194, v194, v195
	v_cvt_pk_bf16_f32 v195, v196, v197
	v_cvt_pk_bf16_f32 v196, v198, v199
	v_cvt_pk_bf16_f32 v197, v200, v201
	v_cvt_pk_bf16_f32 v202, v202, v203
	v_cvt_pk_bf16_f32 v203, v204, v205
	v_cvt_pk_bf16_f32 v204, v206, v207
	v_cvt_pk_bf16_f32 v205, v208, v209
	global_store_dwordx4 v216, v[194:197], s[20:21]
	global_store_dwordx4 v216, v[202:205], s[26:27]
	s_branch .Lwcm0_done
.Lwcm0_tail2:
	s_waitcnt vmcnt(0)
	v_readlane_b32 s20, v221, 8
	v_readlane_b32 s21, v221, 9
	v_readlane_b32 s32, v221, 10
	v_readlane_b32 s35, v221, 11
	ds_write_b32 v210, v146 offset:0
	ds_write_b32 v210, v147 offset:1040
	ds_write_b32 v210, v148 offset:2080
	ds_write_b32 v210, v149 offset:3120
	ds_write_b32 v210, v150 offset:4160
	ds_write_b32 v210, v151 offset:5200
	ds_write_b32 v210, v152 offset:6240
	ds_write_b32 v210, v153 offset:7280
	ds_write_b32 v210, v154 offset:8320
	ds_write_b32 v210, v155 offset:9360
	ds_write_b32 v210, v156 offset:10400
	ds_write_b32 v210, v157 offset:11440
	ds_write_b32 v210, v158 offset:12480
	ds_write_b32 v210, v159 offset:13520
	ds_write_b32 v210, v160 offset:14560
	ds_write_b32 v210, v161 offset:15600
	v_mad_u32_u24 v216, v219, s35, v220
	s_waitcnt lgkmcnt(0)
	s_barrier
	ds_read2_b32 v[194:195], v211 offset1:65
	ds_read2_b32 v[196:197], v211 offset0:130 offset1:195
	ds_read2_b32 v[198:199], v212 offset0:4 offset1:69
	ds_read2_b32 v[200:201], v212 offset0:134 offset1:199
	ds_read2_b32 v[202:203], v213 offset1:65
	ds_read2_b32 v[204:205], v213 offset0:130 offset1:195
	ds_read2_b32 v[206:207], v214 offset0:4 offset1:69
	ds_read2_b32 v[208:209], v214 offset0:134 offset1:199
	s_add_u32 s26, s20, s32
	s_addc_u32 s27, s21, 0
	s_waitcnt lgkmcnt(0)
	s_barrier
	v_cvt_pk_bf16_f32 v194, v194, v195
	v_cvt_pk_bf16_f32 v195, v196, v197
	v_cvt_pk_bf16_f32 v196, v198, v199
	v_cvt_pk_bf16_f32 v197, v200, v201
	v_cvt_pk_bf16_f32 v202, v202, v203
	v_cvt_pk_bf16_f32 v203, v204, v205
	v_cvt_pk_bf16_f32 v204, v206, v207
	v_cvt_pk_bf16_f32 v205, v208, v209
	global_store_dwordx4 v216, v[194:197], s[20:21]
	global_store_dwordx4 v216, v[202:205], s[26:27]
	v_readlane_b32 s20, v221, 12
	v_readlane_b32 s21, v221, 13
	v_readlane_b32 s32, v221, 14
	v_readlane_b32 s35, v221, 15
	ds_write_b32 v210, v162 offset:0
	ds_write_b32 v210, v163 offset:1040
	ds_write_b32 v210, v164 offset:2080
	ds_write_b32 v210, v165 offset:3120
	ds_write_b32 v210, v166 offset:4160
	ds_write_b32 v210, v167 offset:5200
	ds_write_b32 v210, v168 offset:6240
	ds_write_b32 v210, v169 offset:7280
	ds_write_b32 v210, v170 offset:8320
	ds_write_b32 v210, v171 offset:9360
	ds_write_b32 v210, v172 offset:10400
	ds_write_b32 v210, v173 offset:11440
	ds_write_b32 v210, v174 offset:12480
	ds_write_b32 v210, v175 offset:13520
	ds_write_b32 v210, v176 offset:14560
	ds_write_b32 v210, v177 offset:15600
	v_mad_u32_u24 v216, v219, s35, v220
	s_waitcnt lgkmcnt(0)
	s_barrier
	ds_read2_b32 v[194:195], v211 offset1:65
	ds_read2_b32 v[196:197], v211 offset0:130 offset1:195
	ds_read2_b32 v[198:199], v212 offset0:4 offset1:69
	ds_read2_b32 v[200:201], v212 offset0:134 offset1:199
	ds_read2_b32 v[202:203], v213 offset1:65
	ds_read2_b32 v[204:205], v213 offset0:130 offset1:195
	ds_read2_b32 v[206:207], v214 offset0:4 offset1:69
	ds_read2_b32 v[208:209], v214 offset0:134 offset1:199
	s_add_u32 s26, s20, s32
	s_addc_u32 s27, s21, 0
	s_waitcnt lgkmcnt(0)
	s_barrier
	v_cvt_pk_bf16_f32 v194, v194, v195
	v_cvt_pk_bf16_f32 v195, v196, v197
	v_cvt_pk_bf16_f32 v196, v198, v199
	v_cvt_pk_bf16_f32 v197, v200, v201
	v_cvt_pk_bf16_f32 v202, v202, v203
	v_cvt_pk_bf16_f32 v203, v204, v205
	v_cvt_pk_bf16_f32 v204, v206, v207
	v_cvt_pk_bf16_f32 v205, v208, v209
	global_store_dwordx4 v216, v[194:197], s[20:21]
	global_store_dwordx4 v216, v[202:205], s[26:27]
	s_branch .Lwcm0_done

.Lwcm0_p1:
	s_waitcnt vmcnt(0)
	v_readlane_b32 s20, v221, 8
	v_readlane_b32 s21, v221, 9
	v_readlane_b32 s32, v221, 10
	v_readlane_b32 s35, v221, 11
	ds_write_b32 v210, v146 offset:0
	ds_write_b32 v210, v147 offset:1040
	ds_write_b32 v210, v148 offset:2080
	ds_write_b32 v210, v149 offset:3120
	ds_write_b32 v210, v150 offset:4160
	ds_write_b32 v210, v151 offset:5200
	ds_write_b32 v210, v152 offset:6240
	ds_write_b32 v210, v153 offset:7280
	ds_write_b32 v210, v154 offset:8320
	ds_write_b32 v210, v155 offset:9360
	ds_write_b32 v210, v156 offset:10400
	ds_write_b32 v210, v157 offset:11440
	ds_write_b32 v210, v158 offset:12480
	ds_write_b32 v210, v159 offset:13520
	ds_write_b32 v210, v160 offset:14560
	ds_write_b32 v210, v161 offset:15600
	v_mad_u32_u24 v216, v219, s35, v220
	s_waitcnt lgkmcnt(0)
	s_barrier
	ds_read2_b32 v[194:195], v211 offset1:65
	ds_read2_b32 v[196:197], v211 offset0:130 offset1:195
	ds_read2_b32 v[198:199], v212 offset0:4 offset1:69
	ds_read2_b32 v[200:201], v212 offset0:134 offset1:199
	ds_read2_b32 v[202:203], v213 offset1:65
	ds_read2_b32 v[204:205], v213 offset0:130 offset1:195
	ds_read2_b32 v[206:207], v214 offset0:4 offset1:69
	ds_read2_b32 v[208:209], v214 offset0:134 offset1:199
	s_add_u32 s26, s20, s32
	s_addc_u32 s27, s21, 0
	s_waitcnt lgkmcnt(0)
	s_barrier
	v_cvt_pk_bf16_f32 v194, v194, v195
	v_cvt_pk_bf16_f32 v195, v196, v197
	v_cvt_pk_bf16_f32 v196, v198, v199
	v_cvt_pk_bf16_f32 v197, v200, v201
	v_cvt_pk_bf16_f32 v202, v202, v203
	v_cvt_pk_bf16_f32 v203, v204, v205
	v_cvt_pk_bf16_f32 v204, v206, v207
	v_cvt_pk_bf16_f32 v205, v208, v209
	global_store_dwordx4 v216, v[194:197], s[20:21]
	global_store_dwordx4 v216, v[202:205], s[26:27]
.Lwcm0_done:
	s_waitcnt vmcnt(0) lgkmcnt(0)
	s_barrier
	v_readlane_b32 s99, v242, 0
	s_nop 0
	s_sub_u32 s100, s99, 0x100
	s_movk_i32 s23, 96
	s_movk_i32 s22, 0xbc0
	s_waitcnt vmcnt(0) lgkmcnt(0)
	s_barrier
	v_readlane_b32 s0, v242, 42
	v_readlane_b32 s1, v242, 43
	v_readlane_b32 s12, v242, 3
	v_readlane_b32 s13, v242, 4
	v_lshrrev_b32_e32 v217, 6, v137
	v_and_b32_e32 v218, 63, v137
	s_sub_u32 s0, s0, 0x118
	s_subb_u32 s1, s1, 0
	v_lshrrev_b32_e32 v219, 3, v137
	v_and_b32_e32 v220, 7, v137
	v_mul_u32_u24_e32 v210, 65, v217
	v_mul_u32_u24_e32 v211, 0x208, v220
	v_add_u32_e32 v210, v210, v218
	v_add_u32_e32 v211, v211, v219
	v_lshlrev_b32_e32 v210, 2, v210
	v_lshlrev_b32_e32 v211, 2, v211
	v_lshlrev_b32_e32 v218, 2, v218
	v_lshlrev_b32_e32 v220, 4, v220
	v_add_u32_e32 v212, 0x400, v211
	v_add_u32_e32 v213, 0x80, v211
	v_add_u32_e32 v214, 0x480, v211
	s_cmp_ge_u32 s100, s22
	s_cbranch_scc1 .Lwcm1_done
	s_cmpk_ge_u32 s100, 0x900
	s_cbranch_scc1 .Lwcm1_t3_1
	s_cmpk_ge_u32 s100, 0x380
	s_cbranch_scc1 .Lwcm1_t2_1
	s_cmpk_ge_u32 s100, 0x280
	s_cbranch_scc1 .Lwcm1_t1_1
	s_movk_i32 s14, 0x78
	s_sub_u32 s99, s100, 0
	s_mul_i32 s44, s99, 0x66667
	s_lshr_b32 s44, s44, 24
	s_mul_i32 s36, s44, 40
	s_sub_u32 s99, s99, s36
	s_mul_i32 s38, s44, 0xa0000
	s_lshl_b32 s36, s99, 8
	s_add_u32 s38, s38, s36
	s_add_u32 s38, s38, 0xa00000
	s_lshl_b32 s36, s99, 6
	s_mov_b32 s32, 0x10000
	s_mul_i32 s36, s36, 0x800
	s_lshl_b32 s44, s44, 7
	s_add_u32 s36, s36, s44
	s_add_u32 s36, s36, 0x500000
	s_mov_b32 s37, 0xa000
	s_movk_i32 s44, 0x800
	s_mov_b32 s99, 0x2800
	s_branch .Lwcm1_tj_1
.Lwcm1_t1_1:
	s_movk_i32 s14, 0x80
	s_sub_u32 s99, s100, 640
	s_mul_i32 s44, s99, 0x100000
	s_lshr_b32 s44, s44, 24
	s_mul_i32 s36, s44, 16
	s_sub_u32 s99, s99, s36
	s_mul_i32 s38, s44, 0x40000
	s_lshl_b32 s36, s99, 8
	s_add_u32 s38, s38, s36
	s_add_u32 s38, s38, 0x400000
	s_lshl_b32 s36, s99, 6
	s_mov_b32 s32, 0x10000
	s_mul_i32 s36, s36, 0x800
	s_lshl_b32 s44, s44, 7
	s_add_u32 s36, s36, s44
	s_add_u32 s36, s36, 0xc00000
	s_mov_b32 s37, 0x4000
	s_movk_i32 s44, 0x800
	s_mov_b32 s99, 0x1000
	s_branch .Lwcm1_tj_1
.Lwcm1_t2_1:
	s_movk_i32 s14, 0xf0
	s_sub_u32 s99, s100, 896
	s_mul_i32 s44, s99, 0x2e8bb
	s_lshr_b32 s44, s44, 24
	s_mul_i32 s36, s44, 88
	s_sub_u32 s99, s99, s36
	s_mul_i32 s38, s44, 0x160000
	s_lshl_b32 s36, s99, 8
	s_add_u32 s38, s38, s36
	s_add_u32 s38, s38, 0x1600000
	s_cmpk_ge_u32 s99, 44
	s_cselect_b32 s36, 44, 0
	s_cselect_b32 s37, 32, 0
	s_sub_u32 s36, s99, s36
	s_lshl_b32 s36, s36, 7
	s_add_u32 s36, s36, s37
	s_mov_b32 s32, 0x20000
	s_mul_i32 s36, s36, 0x800
	s_lshl_b32 s44, s44, 7
	s_add_u32 s36, s36, s44
	s_add_u32 s36, s36, 0x1900000
	s_mov_b32 s37, 0x16000
	s_movk_i32 s44, 0x800
	s_mov_b32 s99, 0x5800
	s_branch .Lwcm1_tj_1
.Lwcm1_t3_1:
	s_movk_i32 s14, 0xf8
	s_sub_u32 s99, s100, 2304
	s_mul_i32 s44, s99, 0x100000
	s_lshr_b32 s44, s44, 24
	s_mul_i32 s36, s44, 16
	s_sub_u32 s99, s99, s36
	s_mul_i32 s38, s44, 0x40000
	s_lshl_b32 s36, s99, 8
	s_add_u32 s38, s38, s36
	s_add_u32 s38, s38, 0xb00000
	s_lshl_b32 s36, s99, 6
	s_mov_b32 s32, 0x2c000
	s_mul_i32 s36, s36, 0x1600
	s_lshl_b32 s44, s44, 7
	s_add_u32 s36, s36, s44
	s_add_u32 s36, s36, 0x2980000
	s_mov_b32 s37, 0x4000
	s_movk_i32 s44, 0x1600
	s_mov_b32 s99, 0x1000
.Lwcm1_tj_1:
	s_load_dwordx2 s[8:9], s[0:1], s14
	s_add_u32 s20, s12, s36
	s_addc_u32 s21, s13, 0
	v_mad_u32_u24 v215, v217, s99, v218
	v_writelane_b32 v221, s20, 8
	v_writelane_b32 v221, s21, 9
	v_writelane_b32 v221, s32, 10
	v_writelane_b32 v221, s44, 11
	s_add_u32 s100, s100, s23
	s_waitcnt lgkmcnt(0)
	s_add_u32 s38, s8, s38
	s_addc_u32 s39, s9, 0
	global_load_dword v146, v215, s[38:39]
	s_add_u32 s38, s38, s37
	s_addc_u32 s39, s39, 0
	global_load_dword v147, v215, s[38:39]
	s_add_u32 s38, s38, s37
	s_addc_u32 s39, s39, 0
	global_load_dword v148, v215, s[38:39]
	s_add_u32 s38, s38, s37
	s_addc_u32 s39, s39, 0
	global_load_dword v149, v215, s[38:39]
	s_add_u32 s38, s38, s37
	s_addc_u32 s39, s39, 0
	global_load_dword v150, v215, s[38:39]
	s_add_u32 s38, s38, s37
	s_addc_u32 s39, s39, 0
	global_load_dword v151, v215, s[38:39]
	s_add_u32 s38, s38, s37
	s_addc_u32 s39, s39, 0
	global_load_dword v152, v215, s[38:39]
	s_add_u32 s38, s38, s37
	s_addc_u32 s39, s39, 0
	global_load_dword v153, v215, s[38:39]
	s_add_u32 s38, s38, s37
	s_addc_u32 s39, s39, 0
	global_load_dword v154, v215, s[38:39]
	s_add_u32 s38, s38, s37
	s_addc_u32 s39, s39, 0
	global_load_dword v155, v215, s[38:39]
	s_add_u32 s38, s38, s37
	s_addc_u32 s39, s39, 0
	global_load_dword v156, v215, s[38:39]
	s_add_u32 s38, s38, s37
	s_addc_u32 s39, s39, 0
	global_load_dword v157, v215, s[38:39]
	s_add_u32 s38, s38, s37
	s_addc_u32 s39, s39, 0
	global_load_dword v158, v215, s[38:39]
	s_add_u32 s38, s38, s37
	s_addc_u32 s39, s39, 0
	global_load_dword v159, v215, s[38:39]
	s_add_u32 s38, s38, s37
	s_addc_u32 s39, s39, 0
	global_load_dword v160, v215, s[38:39]
	s_add_u32 s38, s38, s37
	s_addc_u32 s39, s39, 0
	global_load_dword v161, v215, s[38:39]
	s_cmp_ge_u32 s100, s22
	s_cbranch_scc1 .Lwcm1_p1
	s_cmpk_ge_u32 s100, 0x900
	s_cbranch_scc1 .Lwcm1_t3_2
	s_cmpk_ge_u32 s100, 0x380
	s_cbranch_scc1 .Lwcm1_t2_2
	s_cmpk_ge_u32 s100, 0x280
	s_cbranch_scc1 .Lwcm1_t1_2
	s_movk_i32 s14, 0x78
	s_sub_u32 s99, s100, 0
	s_mul_i32 s44, s99, 0x66667
	s_lshr_b32 s44, s44, 24
	s_mul_i32 s36, s44, 40
	s_sub_u32 s99, s99, s36
	s_mul_i32 s38, s44, 0xa0000
	s_lshl_b32 s36, s99, 8
	s_add_u32 s38, s38, s36
	s_add_u32 s38, s38, 0xa00000
	s_lshl_b32 s36, s99, 6
	s_mov_b32 s32, 0x10000
	s_mul_i32 s36, s36, 0x800
	s_lshl_b32 s44, s44, 7
	s_add_u32 s36, s36, s44
	s_add_u32 s36, s36, 0x500000
	s_mov_b32 s37, 0xa000
	s_movk_i32 s44, 0x800
	s_mov_b32 s99, 0x2800
	s_branch .Lwcm1_tj_2

.Lwcm1_tj_2:
	s_load_dwordx2 s[8:9], s[0:1], s14
	s_add_u32 s20, s12, s36
	s_addc_u32 s21, s13, 0
	v_mad_u32_u24 v215, v217, s99, v218
	v_writelane_b32 v221, s20, 12
	v_writelane_b32 v221, s21, 13
	v_writelane_b32 v221, s32, 14
	v_writelane_b32 v221, s44, 15
	s_add_u32 s100, s100, s23
	s_waitcnt lgkmcnt(0)
	s_add_u32 s38, s8, s38
	s_addc_u32 s39, s9, 0
	global_load_dword v162, v215, s[38:39]
	s_add_u32 s38, s38, s37
	s_addc_u32 s39, s39, 0
	global_load_dword v163, v215, s[38:39]
	s_add_u32 s38, s38, s37
	s_addc_u32 s39, s39, 0
	global_load_dword v164, v215, s[38:39]
	s_add_u32 s38, s38, s37
	s_addc_u32 s39, s39, 0
	global_load_dword v165, v215, s[38:39]
	s_add_u32 s38, s38, s37
	s_addc_u32 s39, s39, 0
	global_load_dword v166, v215, s[38:39]
	s_add_u32 s38, s38, s37
	s_addc_u32 s39, s39, 0
	global_load_dword v167, v215, s[38:39]
	s_add_u32 s38, s38, s37
	s_addc_u32 s39, s39, 0
	global_load_dword v168, v215, s[38:39]
	s_add_u32 s38, s38, s37
	s_addc_u32 s39, s39, 0
	global_load_dword v169, v215, s[38:39]
	s_add_u32 s38, s38, s37
	s_addc_u32 s39, s39, 0
	global_load_dword v170, v215, s[38:39]
	s_add_u32 s38, s38, s37
	s_addc_u32 s39, s39, 0
	global_load_dword v171, v215, s[38:39]
	s_add_u32 s38, s38, s37
	s_addc_u32 s39, s39, 0
	global_load_dword v172, v215, s[38:39]
	s_add_u32 s38, s38, s37
	s_addc_u32 s39, s39, 0
	global_load_dword v173, v215, s[38:39]
	s_add_u32 s38, s38, s37
	s_addc_u32 s39, s39, 0
	global_load_dword v174, v215, s[38:39]
	s_add_u32 s38, s38, s37
	s_addc_u32 s39, s39, 0
	global_load_dword v175, v215, s[38:39]
	s_add_u32 s38, s38, s37
	s_addc_u32 s39, s39, 0
	global_load_dword v176, v215, s[38:39]
	s_add_u32 s38, s38, s37
	s_addc_u32 s39, s39, 0
	global_load_dword v177, v215, s[38:39]
	s_cmp_ge_u32 s100, s22
	s_cbranch_scc1 .Lwcm1_p2
	s_cmpk_ge_u32 s100, 0x900
	s_cbranch_scc1 .Lwcm1_t3_3
	s_cmpk_ge_u32 s100, 0x380
	s_cbranch_scc1 .Lwcm1_t2_3
	s_cmpk_ge_u32 s100, 0x280
	s_cbranch_scc1 .Lwcm1_t1_3
	s_movk_i32 s14, 0x78
	s_sub_u32 s99, s100, 0
	s_mul_i32 s44, s99, 0x66667
	s_lshr_b32 s44, s44, 24
	s_mul_i32 s36, s44, 40
	s_sub_u32 s99, s99, s36
	s_mul_i32 s38, s44, 0xa0000
	s_lshl_b32 s36, s99, 8
	s_add_u32 s38, s38, s36
	s_add_u32 s38, s38, 0xa00000
	s_lshl_b32 s36, s99, 6
	s_mov_b32 s32, 0x10000
	s_mul_i32 s36, s36, 0x800
	s_lshl_b32 s44, s44, 7
	s_add_u32 s36, s36, s44
	s_add_u32 s36, s36, 0x500000
	s_mov_b32 s37, 0xa000
	s_movk_i32 s44, 0x800
	s_mov_b32 s99, 0x2800
	s_branch .Lwcm1_tj_3

.Lwcm1_loop:
	s_waitcnt vmcnt(32)
	v_readlane_b32 s20, v221, 8
	v_readlane_b32 s21, v221, 9
	v_readlane_b32 s32, v221, 10
	v_readlane_b32 s35, v221, 11
	ds_write_b32 v210, v146 offset:0
	ds_write_b32 v210, v147 offset:1040
	ds_write_b32 v210, v148 offset:2080
	ds_write_b32 v210, v149 offset:3120
	ds_write_b32 v210, v150 offset:4160
	ds_write_b32 v210, v151 offset:5200
	ds_write_b32 v210, v152 offset:6240
	ds_write_b32 v210, v153 offset:7280
	ds_write_b32 v210, v154 offset:8320
	ds_write_b32 v210, v155 offset:9360
	ds_write_b32 v210, v156 offset:10400
	ds_write_b32 v210, v157 offset:11440
	ds_write_b32 v210, v158 offset:12480
	ds_write_b32 v210, v159 offset:13520
	ds_write_b32 v210, v160 offset:14560
	ds_write_b32 v210, v161 offset:15600
	v_mad_u32_u24 v216, v219, s35, v220
	s_waitcnt lgkmcnt(0)
	s_barrier
	ds_read2_b32 v[194:195], v211 offset1:65
	ds_read2_b32 v[196:197], v211 offset0:130 offset1:195
	ds_read2_b32 v[198:199], v212 offset0:4 offset1:69
	ds_read2_b32 v[200:201], v212 offset0:134 offset1:199
	ds_read2_b32 v[202:203], v213 offset1:65
	ds_read2_b32 v[204:205], v213 offset0:130 offset1:195
	ds_read2_b32 v[206:207], v214 offset0:4 offset1:69
	ds_read2_b32 v[208:209], v214 offset0:134 offset1:199
	s_add_u32 s26, s20, s32
	s_addc_u32 s27, s21, 0
	s_waitcnt lgkmcnt(0)
	s_barrier
	v_cvt_pk_bf16_f32 v194, v194, v195
	v_cvt_pk_bf16_f32 v195, v196, v197
	v_cvt_pk_bf16_f32 v196, v198, v199
	v_cvt_pk_bf16_f32 v197, v200, v201
	v_cvt_pk_bf16_f32 v202, v202, v203
	v_cvt_pk_bf16_f32 v203, v204, v205
	v_cvt_pk_bf16_f32 v204, v206, v207
	v_cvt_pk_bf16_f32 v205, v208, v209
	global_store_dwordx4 v216, v[194:197], s[20:21]
	global_store_dwordx4 v216, v[202:205], s[26:27]
	s_cmp_ge_u32 s100, s22
	s_cbranch_scc1 .Lwcm1_tail0
	s_cmpk_ge_u32 s100, 0x900
	s_cbranch_scc1 .Lwcm1_t3_4
	s_cmpk_ge_u32 s100, 0x380
	s_cbranch_scc1 .Lwcm1_t2_4
	s_cmpk_ge_u32 s100, 0x280
	s_cbranch_scc1 .Lwcm1_t1_4
	s_movk_i32 s14, 0x78
	s_sub_u32 s99, s100, 0
	s_mul_i32 s44, s99, 0x66667
	s_lshr_b32 s44, s44, 24
	s_mul_i32 s36, s44, 40
	s_sub_u32 s99, s99, s36
	s_mul_i32 s38, s44, 0xa0000
	s_lshl_b32 s36, s99, 8
	s_add_u32 s38, s38, s36
	s_add_u32 s38, s38, 0xa00000
	s_lshl_b32 s36, s99, 6
	s_mov_b32 s32, 0x10000
	s_mul_i32 s36, s36, 0x800
	s_lshl_b32 s44, s44, 7
	s_add_u32 s36, s36, s44
	s_add_u32 s36, s36, 0x500000
	s_mov_b32 s37, 0xa000
	s_movk_i32 s44, 0x800
	s_mov_b32 s99, 0x2800
	s_branch .Lwcm1_tj_4

.Lwcm1_tj_4:
	s_load_dwordx2 s[8:9], s[0:1], s14
	s_add_u32 s20, s12, s36
	s_addc_u32 s21, s13, 0
	v_mad_u32_u24 v215, v217, s99, v218
	v_writelane_b32 v221, s20, 8
	v_writelane_b32 v221, s21, 9
	v_writelane_b32 v221, s32, 10
	v_writelane_b32 v221, s44, 11
	s_add_u32 s100, s100, s23
	s_waitcnt lgkmcnt(0)
	s_add_u32 s38, s8, s38
	s_addc_u32 s39, s9, 0
	global_load_dword v146, v215, s[38:39]
	s_add_u32 s38, s38, s37
	s_addc_u32 s39, s39, 0
	global_load_dword v147, v215, s[38:39]
	s_add_u32 s38, s38, s37
	s_addc_u32 s39, s39, 0
	global_load_dword v148, v215, s[38:39]
	s_add_u32 s38, s38, s37
	s_addc_u32 s39, s39, 0
	global_load_dword v149, v215, s[38:39]
	s_add_u32 s38, s38, s37
	s_addc_u32 s39, s39, 0
	global_load_dword v150, v215, s[38:39]
	s_add_u32 s38, s38, s37
	s_addc_u32 s39, s39, 0
	global_load_dword v151, v215, s[38:39]
	s_add_u32 s38, s38, s37
	s_addc_u32 s39, s39, 0
	global_load_dword v152, v215, s[38:39]
	s_add_u32 s38, s38, s37
	s_addc_u32 s39, s39, 0
	global_load_dword v153, v215, s[38:39]
	s_add_u32 s38, s38, s37
	s_addc_u32 s39, s39, 0
	global_load_dword v154, v215, s[38:39]
	s_add_u32 s38, s38, s37
	s_addc_u32 s39, s39, 0
	global_load_dword v155, v215, s[38:39]
	s_add_u32 s38, s38, s37
	s_addc_u32 s39, s39, 0
	global_load_dword v156, v215, s[38:39]
	s_add_u32 s38, s38, s37
	s_addc_u32 s39, s39, 0
	global_load_dword v157, v215, s[38:39]
	s_add_u32 s38, s38, s37
	s_addc_u32 s39, s39, 0
	global_load_dword v158, v215, s[38:39]
	s_add_u32 s38, s38, s37
	s_addc_u32 s39, s39, 0
	global_load_dword v159, v215, s[38:39]
	s_add_u32 s38, s38, s37
	s_addc_u32 s39, s39, 0
	global_load_dword v160, v215, s[38:39]
	s_add_u32 s38, s38, s37
	s_addc_u32 s39, s39, 0
	global_load_dword v161, v215, s[38:39]
	s_waitcnt vmcnt(32)
	v_readlane_b32 s20, v221, 12
	v_readlane_b32 s21, v221, 13
	v_readlane_b32 s32, v221, 14
	v_readlane_b32 s35, v221, 15
	ds_write_b32 v210, v162 offset:0
	ds_write_b32 v210, v163 offset:1040
	ds_write_b32 v210, v164 offset:2080
	ds_write_b32 v210, v165 offset:3120
	ds_write_b32 v210, v166 offset:4160
	ds_write_b32 v210, v167 offset:5200
	ds_write_b32 v210, v168 offset:6240
	ds_write_b32 v210, v169 offset:7280
	ds_write_b32 v210, v170 offset:8320
	ds_write_b32 v210, v171 offset:9360
	ds_write_b32 v210, v172 offset:10400
	ds_write_b32 v210, v173 offset:11440
	ds_write_b32 v210, v174 offset:12480
	ds_write_b32 v210, v175 offset:13520
	ds_write_b32 v210, v176 offset:14560
	ds_write_b32 v210, v177 offset:15600
	v_mad_u32_u24 v216, v219, s35, v220
	s_waitcnt lgkmcnt(0)
	s_barrier
	ds_read2_b32 v[194:195], v211 offset1:65
	ds_read2_b32 v[196:197], v211 offset0:130 offset1:195
	ds_read2_b32 v[198:199], v212 offset0:4 offset1:69
	ds_read2_b32 v[200:201], v212 offset0:134 offset1:199
	ds_read2_b32 v[202:203], v213 offset1:65
	ds_read2_b32 v[204:205], v213 offset0:130 offset1:195
	ds_read2_b32 v[206:207], v214 offset0:4 offset1:69
	ds_read2_b32 v[208:209], v214 offset0:134 offset1:199
	s_add_u32 s26, s20, s32
	s_addc_u32 s27, s21, 0
	s_waitcnt lgkmcnt(0)
	s_barrier
	v_cvt_pk_bf16_f32 v194, v194, v195
	v_cvt_pk_bf16_f32 v195, v196, v197
	v_cvt_pk_bf16_f32 v196, v198, v199
	v_cvt_pk_bf16_f32 v197, v200, v201
	v_cvt_pk_bf16_f32 v202, v202, v203
	v_cvt_pk_bf16_f32 v203, v204, v205
	v_cvt_pk_bf16_f32 v204, v206, v207
	v_cvt_pk_bf16_f32 v205, v208, v209
	global_store_dwordx4 v216, v[194:197], s[20:21]
	global_store_dwordx4 v216, v[202:205], s[26:27]
	s_cmp_ge_u32 s100, s22
	s_cbranch_scc1 .Lwcm1_tail1
	s_cmpk_ge_u32 s100, 0x900
	s_cbranch_scc1 .Lwcm1_t3_5
	s_cmpk_ge_u32 s100, 0x380
	s_cbranch_scc1 .Lwcm1_t2_5
	s_cmpk_ge_u32 s100, 0x280
	s_cbranch_scc1 .Lwcm1_t1_5
	s_movk_i32 s14, 0x78
	s_sub_u32 s99, s100, 0
	s_mul_i32 s44, s99, 0x66667
	s_lshr_b32 s44, s44, 24
	s_mul_i32 s36, s44, 40
	s_sub_u32 s99, s99, s36
	s_mul_i32 s38, s44, 0xa0000
	s_lshl_b32 s36, s99, 8
	s_add_u32 s38, s38, s36
	s_add_u32 s38, s38, 0xa00000
	s_lshl_b32 s36, s99, 6
	s_mov_b32 s32, 0x10000
	s_mul_i32 s36, s36, 0x800
	s_lshl_b32 s44, s44, 7
	s_add_u32 s36, s36, s44
	s_add_u32 s36, s36, 0x500000
	s_mov_b32 s37, 0xa000
	s_movk_i32 s44, 0x800
	s_mov_b32 s99, 0x2800
	s_branch .Lwcm1_tj_5

.Lwcm1_tj_5:
	s_load_dwordx2 s[8:9], s[0:1], s14
	s_add_u32 s20, s12, s36
	s_addc_u32 s21, s13, 0
	v_mad_u32_u24 v215, v217, s99, v218
	v_writelane_b32 v221, s20, 12
	v_writelane_b32 v221, s21, 13
	v_writelane_b32 v221, s32, 14
	v_writelane_b32 v221, s44, 15
	s_add_u32 s100, s100, s23
	s_waitcnt lgkmcnt(0)
	s_add_u32 s38, s8, s38
	s_addc_u32 s39, s9, 0
	global_load_dword v162, v215, s[38:39]
	s_add_u32 s38, s38, s37
	s_addc_u32 s39, s39, 0
	global_load_dword v163, v215, s[38:39]
	s_add_u32 s38, s38, s37
	s_addc_u32 s39, s39, 0
	global_load_dword v164, v215, s[38:39]
	s_add_u32 s38, s38, s37
	s_addc_u32 s39, s39, 0
	global_load_dword v165, v215, s[38:39]
	s_add_u32 s38, s38, s37
	s_addc_u32 s39, s39, 0
	global_load_dword v166, v215, s[38:39]
	s_add_u32 s38, s38, s37
	s_addc_u32 s39, s39, 0
	global_load_dword v167, v215, s[38:39]
	s_add_u32 s38, s38, s37
	s_addc_u32 s39, s39, 0
	global_load_dword v168, v215, s[38:39]
	s_add_u32 s38, s38, s37
	s_addc_u32 s39, s39, 0
	global_load_dword v169, v215, s[38:39]
	s_add_u32 s38, s38, s37
	s_addc_u32 s39, s39, 0
	global_load_dword v170, v215, s[38:39]
	s_add_u32 s38, s38, s37
	s_addc_u32 s39, s39, 0
	global_load_dword v171, v215, s[38:39]
	s_add_u32 s38, s38, s37
	s_addc_u32 s39, s39, 0
	global_load_dword v172, v215, s[38:39]
	s_add_u32 s38, s38, s37
	s_addc_u32 s39, s39, 0
	global_load_dword v173, v215, s[38:39]
	s_add_u32 s38, s38, s37
	s_addc_u32 s39, s39, 0
	global_load_dword v174, v215, s[38:39]
	s_add_u32 s38, s38, s37
	s_addc_u32 s39, s39, 0
	global_load_dword v175, v215, s[38:39]
	s_add_u32 s38, s38, s37
	s_addc_u32 s39, s39, 0
	global_load_dword v176, v215, s[38:39]
	s_add_u32 s38, s38, s37
	s_addc_u32 s39, s39, 0
	global_load_dword v177, v215, s[38:39]
	s_waitcnt vmcnt(32)
	v_readlane_b32 s20, v221, 16
	v_readlane_b32 s21, v221, 17
	v_readlane_b32 s32, v221, 18
	v_readlane_b32 s35, v221, 19
	ds_write_b32 v210, v178 offset:0
	ds_write_b32 v210, v179 offset:1040
	ds_write_b32 v210, v180 offset:2080
	ds_write_b32 v210, v181 offset:3120
	ds_write_b32 v210, v182 offset:4160
	ds_write_b32 v210, v183 offset:5200
	ds_write_b32 v210, v184 offset:6240
	ds_write_b32 v210, v185 offset:7280
	ds_write_b32 v210, v186 offset:8320
	ds_write_b32 v210, v187 offset:9360
	ds_write_b32 v210, v188 offset:10400
	ds_write_b32 v210, v189 offset:11440
	ds_write_b32 v210, v190 offset:12480
	ds_write_b32 v210, v191 offset:13520
	ds_write_b32 v210, v192 offset:14560
	ds_write_b32 v210, v193 offset:15600
	v_mad_u32_u24 v216, v219, s35, v220
	s_waitcnt lgkmcnt(0)
	s_barrier
	ds_read2_b32 v[194:195], v211 offset1:65
	ds_read2_b32 v[196:197], v211 offset0:130 offset1:195
	ds_read2_b32 v[198:199], v212 offset0:4 offset1:69
	ds_read2_b32 v[200:201], v212 offset0:134 offset1:199
	ds_read2_b32 v[202:203], v213 offset1:65
	ds_read2_b32 v[204:205], v213 offset0:130 offset1:195
	ds_read2_b32 v[206:207], v214 offset0:4 offset1:69
	ds_read2_b32 v[208:209], v214 offset0:134 offset1:199
	s_add_u32 s26, s20, s32
	s_addc_u32 s27, s21, 0
	s_waitcnt lgkmcnt(0)
	s_barrier
	v_cvt_pk_bf16_f32 v194, v194, v195
	v_cvt_pk_bf16_f32 v195, v196, v197
	v_cvt_pk_bf16_f32 v196, v198, v199
	v_cvt_pk_bf16_f32 v197, v200, v201
	v_cvt_pk_bf16_f32 v202, v202, v203
	v_cvt_pk_bf16_f32 v203, v204, v205
	v_cvt_pk_bf16_f32 v204, v206, v207
	v_cvt_pk_bf16_f32 v205, v208, v209
	global_store_dwordx4 v216, v[194:197], s[20:21]
	global_store_dwordx4 v216, v[202:205], s[26:27]
	s_cmp_ge_u32 s100, s22
	s_cbranch_scc1 .Lwcm1_tail2
	s_cmpk_ge_u32 s100, 0x900
	s_cbranch_scc1 .Lwcm1_t3_6
	s_cmpk_ge_u32 s100, 0x380
	s_cbranch_scc1 .Lwcm1_t2_6
	s_cmpk_ge_u32 s100, 0x280
	s_cbranch_scc1 .Lwcm1_t1_6
	s_movk_i32 s14, 0x78
	s_sub_u32 s99, s100, 0
	s_mul_i32 s44, s99, 0x66667
	s_lshr_b32 s44, s44, 24
	s_mul_i32 s36, s44, 40
	s_sub_u32 s99, s99, s36
	s_mul_i32 s38, s44, 0xa0000
	s_lshl_b32 s36, s99, 8
	s_add_u32 s38, s38, s36
	s_add_u32 s38, s38, 0xa00000
	s_lshl_b32 s36, s99, 6
	s_mov_b32 s32, 0x10000
	s_mul_i32 s36, s36, 0x800
	s_lshl_b32 s44, s44, 7
	s_add_u32 s36, s36, s44
	s_add_u32 s36, s36, 0x500000
	s_mov_b32 s37, 0xa000
	s_movk_i32 s44, 0x800
	s_mov_b32 s99, 0x2800
	s_branch .Lwcm1_tj_6

.Lwcm_skip:
	v_readlane_b32 s1, v242, 61
	v_readlane_b32 s2, v242, 62
	v_readlane_b32 s3, v242, 63
	v_writelane_b32 v241, s73, 19
	s_branch .LBB0_909
